# ssd_sample: first two heads' state loads issued at item start (overlap the setup)
# baseline (speedup 1.0000x reference)
.LBB0_290:
	s_ashr_i32 s96, s33, 1
	s_lshl_b32 s96, s96, 19
	s_and_b32 s97, s33, 1
	s_lshl_b32 s97, s97, 18
	s_or_b32 s96, s96, s97
	v_readlane_b32 s34, v242, 29
	v_readlane_b32 s35, v242, 30
	v_lshrrev_b32_e32 v252, 3, v0
	v_and_b32_e32 v253, 7, v0
	v_lshlrev_b32_e32 v252, 9, v252
	v_lshl_or_b32 v252, v253, 6, v252
	s_add_u32 s34, s34, s96
	s_addc_u32 s35, s35, 0
	s_add_u32 s96, s34, 0x8000
	s_addc_u32 s97, s35, 0
	global_load_dwordx4 v[186:189], v252, s[34:35] offset:48
	global_load_dwordx4 v[190:193], v252, s[34:35] offset:32
	global_load_dwordx4 v[194:197], v252, s[34:35] offset:16
	global_load_dwordx4 v[202:205], v252, s[34:35]
	global_load_dwordx4 v[206:209], v252, s[96:97]
	global_load_dwordx4 v[210:213], v252, s[96:97] offset:48
	global_load_dwordx4 v[214:217], v252, s[96:97] offset:32
	global_load_dwordx4 v[248:251], v252, s[96:97] offset:16
	s_ashr_i32 s8, s33, 1
	s_ashr_i32 s9, s8, 31
	s_and_b32 s4, s33, 1
	s_lshl_b64 s[6:7], s[8:9], 2
	v_mov_b32_e32 v75, v0
	s_add_u32 s6, s6, 0x4000
	s_movk_i32 s10, 0x300
	s_addc_u32 s7, s7, 0
	v_cmp_gt_i32_e32 vcc, s10, v75
	v_cndmask_b32_e64 v20, 0, 1, s[52:53]
	s_and_saveexec_b64 s[10:11], vcc
	s_cbranch_execz .LBB0_301
	s_lshl_b32 s34, s4, 7
	s_mul_i32 s12, s7, 0x2400
	s_mul_hi_u32 s13, s6, 0x2400
	s_bitset1_b32 s34, 10
	s_lshl_b32 s35, s4, 9
	s_add_i32 s13, s13, s12
	s_mul_i32 s12, s6, 0x2400
	s_add_u32 s12, s60, s12
	s_addc_u32 s13, s61, s13
	s_add_u32 s12, s12, 0x1000
	s_addc_u32 s13, s13, 0
	s_mul_i32 s15, s8, 0x9000
	s_mul_hi_i32 s14, s8, 0x9000
	s_add_u32 s18, s60, s15
	s_addc_u32 s19, s61, s14
	s_add_u32 s14, s18, 0x9003400
	s_addc_u32 s15, s19, 0
	s_add_u32 s16, s18, 0x9005800
	s_addc_u32 s17, s19, 0
	s_add_u32 s18, s18, 0x9007c00
	v_readlane_b32 s36, v242, 21
	s_mul_i32 s20, s8, 0x4800
	s_addc_u32 s19, s19, 0
	v_readlane_b32 s46, v242, 31
	v_lshlrev_b32_e32 v2, 7, v20
	s_mul_hi_i32 s21, s8, 0x4800
	v_readlane_b32 s47, v242, 32
	s_add_u32 s20, s46, s20
	v_add_u32_e32 v4, 0x280, v2
	s_addc_u32 s21, s47, s21
	s_mov_b64 s[22:23], 0
	v_mov_b32_e32 v5, v75
	v_readlane_b32 s37, v242, 22
	v_readlane_b32 s38, v242, 23
	v_readlane_b32 s39, v242, 24
	v_readlane_b32 s40, v242, 25
	v_readlane_b32 s41, v242, 26
	v_readlane_b32 s42, v242, 27
	v_readlane_b32 s43, v242, 28
	v_readlane_b32 s44, v242, 29
	v_readlane_b32 s45, v242, 30
	v_readlane_b32 s48, v242, 33
	v_readlane_b32 s49, v242, 34
	v_readlane_b32 s50, v242, 35
	v_readlane_b32 s51, v242, 36
	s_branch .LBB0_293

.LBB0_310:
	s_or_b64 exec, exec, s[10:11]
	s_lshl_b32 s10, s14, 15
	s_lshl_b64 s[8:9], s[8:9], 19
	v_readlane_b32 s12, v242, 21
	s_or_b32 s10, s8, s10
	v_readlane_b32 s20, v242, 29
	v_readlane_b32 s36, v242, 2
	v_readlane_b32 s21, v242, 30
	s_add_u32 s10, s20, s10
	v_lshlrev_b32_e32 v50, 5, v20
	v_readlane_b32 s48, v242, 14
	v_readlane_b32 s49, v242, 15
	s_addc_u32 s11, s21, s9
	v_lshlrev_b64 v[22:23], 9, v[2:3]
	v_lshl_add_u64 v[54:55], s[48:49], 0, v[50:51]
	v_lshl_add_u64 v[2:3], s[10:11], 0, v[22:23]
	v_lshlrev_b32_e32 v50, 6, v21
	v_lshl_add_u64 v[2:3], v[2:3], 0, v[50:51]
	s_mov_b64 s[10:11], 0x8000
	v_lshl_add_u64 v[14:15], v[2:3], 0, s[10:11]
	s_mov_b32 s10, 0x8000
	s_waitcnt lgkmcnt(0)
	s_barrier
	s_waitcnt vmcnt(0)
	v_mov_b32_e32 v34, v186
	v_mov_b32_e32 v35, v187
	v_mov_b32_e32 v36, v188
	v_mov_b32_e32 v37, v189
	v_mov_b32_e32 v38, v190
	v_mov_b32_e32 v39, v191
	v_mov_b32_e32 v40, v192
	v_mov_b32_e32 v41, v193
	v_mov_b32_e32 v42, v194
	v_mov_b32_e32 v43, v195
	v_mov_b32_e32 v44, v196
	v_mov_b32_e32 v45, v197
	v_mov_b32_e32 v46, v202
	v_mov_b32_e32 v47, v203
	v_mov_b32_e32 v48, v204
	v_mov_b32_e32 v49, v205
	v_add_co_u32_e32 v2, vcc, s10, v2
	v_lshlrev_b32_e32 v19, 18, v20
	s_nop 0
	v_addc_co_u32_e32 v3, vcc, 0, v3, vcc
	v_mov_b32_e32 v10, v206
	v_mov_b32_e32 v11, v207
	v_mov_b32_e32 v12, v208
	v_mov_b32_e32 v13, v209
	s_nop 0
	v_mov_b32_e32 v2, v210
	v_mov_b32_e32 v3, v211
	v_mov_b32_e32 v4, v212
	v_mov_b32_e32 v5, v213
	v_mov_b32_e32 v6, v214
	v_mov_b32_e32 v7, v215
	v_mov_b32_e32 v8, v216
	v_mov_b32_e32 v9, v217
	s_nop 0
	v_mov_b32_e32 v14, v248
	v_mov_b32_e32 v15, v249
	v_mov_b32_e32 v16, v250
	v_mov_b32_e32 v17, v251
	v_lshl_add_u32 v53, v18, 2, 0
	v_or_b32_e32 v18, s8, v19
	v_mov_b32_e32 v19, s9
	v_lshl_add_u64 v[18:19], v[18:19], 0, v[22:23]
	v_readlane_b32 s13, v242, 22
	v_lshl_or_b32 v18, v21, 6, v18
	s_mov_b32 s12, 0
	v_add_u32_e32 v50, 0, v50
	v_cmp_eq_u32_e32 vcc, 0, v21
	v_lshl_add_u64 v[56:57], s[0:1], 0, v[18:19]
	v_lshl_add_u64 v[58:59], s[2:3], 0, v[18:19]
	s_add_i32 s13, 0, 0x3000
	s_mov_b64 s[8:9], 0
	v_readlane_b32 s37, v242, 3
	v_readlane_b32 s38, v242, 4
	v_readlane_b32 s39, v242, 5
	v_readlane_b32 s40, v242, 6
	v_readlane_b32 s41, v242, 7
	v_readlane_b32 s42, v242, 8
	v_readlane_b32 s43, v242, 9
	v_readlane_b32 s44, v242, 10
	v_readlane_b32 s45, v242, 11
	v_readlane_b32 s46, v242, 12
	v_readlane_b32 s47, v242, 13
	v_readlane_b32 s50, v242, 16
	v_readlane_b32 s51, v242, 17
	v_readlane_b32 s14, v242, 23
	v_readlane_b32 s15, v242, 24
	v_readlane_b32 s16, v242, 25
	v_readlane_b32 s17, v242, 26
	v_readlane_b32 s18, v242, 27
	v_readlane_b32 s19, v242, 28
	v_readlane_b32 s22, v242, 31
	v_readlane_b32 s23, v242, 32
	v_readlane_b32 s24, v242, 33
	v_readlane_b32 s25, v242, 34
	v_readlane_b32 s26, v242, 35
	v_readlane_b32 s27, v242, 36
	global_load_dword v200, v[54:55], off
	s_waitcnt vmcnt(0)
	s_branch .LBB0_312
